# converted-weight stores (16 B per lane, P0 and P4 conversion routines) written through (sc1) so the seams' L2 write-back has less to flush
# baseline (speedup 1.0000x reference)
.LBB0_32:
	s_cmpk_gt_i32 s3, 0x7ff
	s_mov_b64 s[4:5], -1
	s_cbranch_scc0 .LBB0_38
	s_cmpk_gt_u32 s3, 0xbff
	s_cbranch_scc0 .LBB0_35
	s_add_i32 s0, s3, 0xfffff400
	s_lshr_b32 s6, s0, 4
	s_lshl_b64 s[0:1], s[6:7], 18
	s_add_u32 s4, s38, s0
	s_addc_u32 s5, s39, s1
	s_lshl_b64 s[0:1], s[6:7], 17
	s_add_u32 s6, s10, s0
	s_addc_u32 s1, s11, s1
	s_add_i32 s0, s12, 0x400
	s_and_b32 s0, s0, 0xc0
	s_and_b32 s8, s14, 0xc0
	s_lshl_b32 s9, s0, 2
	s_add_u32 s4, s4, s9
	v_or_b32_e32 v0, s8, v16
	s_addc_u32 s5, s5, 0
	v_mov_b32_e32 v11, v1
	v_lshl_add_u64 v[14:15], s[4:5], 0, v[10:11]
	v_lshlrev_b32_e32 v0, 10, v0
	v_lshl_add_u64 v[14:15], v[14:15], 0, v[0:1]
	v_add_co_u32_e32 v60, vcc, s22, v14
	v_add_u32_e32 v0, 0x3cf0, v17
	s_nop 0
	v_addc_co_u32_e32 v61, vcc, 0, v15, vcc
	v_add_co_u32_e32 v62, vcc, s23, v14
	v_add_u32_e32 v11, 0x400, v19
	s_nop 0
	v_addc_co_u32_e32 v63, vcc, 0, v15, vcc
	v_add_co_u32_e32 v66, vcc, s28, v14
	global_load_dwordx2 v[64:65], v[62:63], off offset:-4096 nt
	s_nop 0
	v_addc_co_u32_e32 v67, vcc, 0, v15, vcc
	v_add_co_u32_e32 v68, vcc, s29, v14
	s_lshl_b32 s4, s8, 1
	s_nop 0
	v_addc_co_u32_e32 v69, vcc, 0, v15, vcc
	v_add_co_u32_e32 v80, vcc, s33, v14
	global_load_dwordx2 v[70:71], v[14:15], off nt
	global_load_dwordx2 v[72:73], v[14:15], off offset:2048 nt
	s_nop 0
	global_load_dwordx2 v[60:61], v[60:61], off offset:2048 nt
	s_nop 0
	global_load_dwordx2 v[66:67], v[66:67], off offset:2048 nt
	s_nop 0
	global_load_dwordx2 v[74:75], v[62:63], off nt
	s_nop 0
	global_load_dwordx2 v[62:63], v[62:63], off offset:2048 nt
	s_nop 0
	global_load_dwordx2 v[76:77], v[68:69], off offset:-4096 nt
	global_load_dwordx2 v[78:79], v[68:69], off nt
	v_addc_co_u32_e32 v81, vcc, 0, v15, vcc
	v_add_co_u32_e32 v82, vcc, s40, v14
	s_add_u32 s4, s6, s4
	s_nop 0
	v_addc_co_u32_e32 v83, vcc, 0, v15, vcc
	v_add_co_u32_e32 v88, vcc, s41, v14
	global_load_dwordx2 v[68:69], v[68:69], off offset:2048 nt
	s_nop 0
	global_load_dwordx2 v[84:85], v[82:83], off offset:-4096 nt
	global_load_dwordx2 v[86:87], v[82:83], off nt
	s_nop 0
	global_load_dwordx2 v[82:83], v[82:83], off offset:2048 nt
	v_addc_co_u32_e32 v89, vcc, 0, v15, vcc
	v_add_co_u32_e32 v90, vcc, s42, v14
	s_addc_u32 s5, s1, 0
	s_nop 0
	v_addc_co_u32_e32 v91, vcc, 0, v15, vcc
	v_add_co_u32_e32 v92, vcc, s43, v14
	v_mov_b32_e32 v13, v1
	s_nop 0
	v_addc_co_u32_e32 v93, vcc, 0, v15, vcc
	v_add_co_u32_e32 v94, vcc, s46, v14
	s_nop 1
	v_addc_co_u32_e32 v95, vcc, 0, v15, vcc
	v_add_co_u32_e32 v102, vcc, s47, v14
	global_load_dwordx2 v[96:97], v[90:91], off offset:-4096 nt
	global_load_dwordx2 v[98:99], v[90:91], off nt
	s_nop 0
	global_load_dwordx2 v[90:91], v[90:91], off offset:2048 nt
	s_nop 0
	global_load_dwordx2 v[100:101], v[94:95], off offset:-4096 nt
	v_addc_co_u32_e32 v103, vcc, 0, v15, vcc
	v_add_co_u32_e32 v104, vcc, s48, v14
	s_nop 1
	v_addc_co_u32_e32 v105, vcc, 0, v15, vcc
	v_add_co_u32_e32 v112, vcc, s49, v14
	global_load_dwordx2 v[80:81], v[80:81], off offset:2048 nt
	s_nop 0
	global_load_dwordx2 v[88:89], v[88:89], off offset:2048 nt
	s_nop 0
	global_load_dwordx2 v[92:93], v[92:93], off offset:2048 nt
	s_nop 0
	global_load_dwordx2 v[102:103], v[102:103], off offset:2048 nt
	s_nop 0
	global_load_dwordx2 v[106:107], v[94:95], off nt
	s_nop 0
	global_load_dwordx2 v[94:95], v[94:95], off offset:2048 nt
	s_nop 0
	global_load_dwordx2 v[108:109], v[104:105], off offset:-4096 nt
	global_load_dwordx2 v[110:111], v[104:105], off nt
	v_addc_co_u32_e32 v113, vcc, 0, v15, vcc
	v_add_co_u32_e32 v114, vcc, s50, v14
	s_nop 1
	v_addc_co_u32_e32 v115, vcc, 0, v15, vcc
	v_add_co_u32_e32 v14, vcc, s51, v14
	global_load_dwordx2 v[112:113], v[112:113], off offset:2048 nt
	s_nop 0
	global_load_dwordx2 v[104:105], v[104:105], off offset:2048 nt
	s_nop 0
	global_load_dwordx2 v[116:117], v[114:115], off offset:-4096 nt
	global_load_dwordx2 v[118:119], v[114:115], off nt
	s_nop 0
	global_load_dwordx2 v[114:115], v[114:115], off offset:2048 nt
	v_addc_co_u32_e32 v15, vcc, 0, v15, vcc
	global_load_dwordx2 v[120:121], v[14:15], off nt
	s_nop 0
	global_load_dwordx2 v[14:15], v[14:15], off offset:2048 nt
	s_waitcnt vmcnt(30)
	ds_write2_b32 v17, v70, v71 offset1:1
	s_waitcnt vmcnt(29)
	ds_write2_b32 v17, v72, v73 offset0:130 offset1:131
	ds_write2_b32 v30, v64, v65 offset1:1
	s_waitcnt vmcnt(28)
	ds_write2_b32 v31, v60, v61 offset1:1
	s_waitcnt vmcnt(26)
	ds_write2_b32 v32, v74, v75 offset1:1
	s_waitcnt vmcnt(25)
	ds_write2_b32 v33, v62, v63 offset1:1
	s_waitcnt vmcnt(24)
	ds_write2_b32 v34, v76, v77 offset1:1
	ds_write2_b32 v35, v66, v67 offset1:1
	s_waitcnt vmcnt(23)
	ds_write2_b32 v36, v78, v79 offset1:1
	s_waitcnt vmcnt(22)
	ds_write2_b32 v37, v68, v69 offset1:1
	s_waitcnt vmcnt(21)
	ds_write2_b32 v38, v84, v85 offset1:1
	s_waitcnt vmcnt(14)
	ds_write2_b32 v39, v80, v81 offset1:1
	ds_write2_b32 v40, v86, v87 offset1:1
	ds_write2_b32 v41, v82, v83 offset1:1
	ds_write2_b32 v42, v96, v97 offset1:1
	s_waitcnt vmcnt(13)
	ds_write2_b32 v43, v88, v89 offset1:1
	ds_write2_b32 v44, v98, v99 offset1:1
	ds_write2_b32 v45, v90, v91 offset1:1
	ds_write2_b32 v46, v100, v101 offset1:1
	s_waitcnt vmcnt(12)
	ds_write2_b32 v47, v92, v93 offset1:1
	s_waitcnt vmcnt(10)
	ds_write2_b32 v48, v106, v107 offset1:1
	s_waitcnt vmcnt(9)
	ds_write2_b32 v49, v94, v95 offset1:1
	s_waitcnt vmcnt(8)
	ds_write2_b32 v50, v108, v109 offset1:1
	ds_write2_b32 v51, v102, v103 offset1:1
	s_waitcnt vmcnt(7)
	ds_write2_b32 v52, v110, v111 offset1:1
	s_waitcnt vmcnt(5)
	ds_write2_b32 v53, v104, v105 offset1:1
	s_waitcnt vmcnt(4)
	ds_write2_b32 v54, v116, v117 offset1:1
	ds_write2_b32 v55, v112, v113 offset1:1
	s_waitcnt vmcnt(3)
	ds_write2_b32 v56, v118, v119 offset1:1
	s_waitcnt vmcnt(2)
	ds_write2_b32 v57, v114, v115 offset1:1
	v_lshl_add_u64 v[78:79], s[4:5], 0, v[12:13]
	s_waitcnt vmcnt(1)
	ds_write2_b32 v0, v120, v121 offset1:1
	v_add_u32_e32 v0, 0x3ef8, v17
	s_waitcnt vmcnt(0)
	ds_write2_b32 v0, v14, v15 offset1:1
	s_waitcnt lgkmcnt(0)
	ds_read2_b32 v[14:15], v19 offset0:65 offset1:73
	ds_read2_b32 v[64:65], v19 offset1:8
	ds_read2_b32 v[66:67], v19 offset0:130 offset1:138
	ds_read2_b32 v[68:69], v19 offset0:195 offset1:203
	ds_read2_b32 v[70:71], v11 offset0:4 offset1:12
	ds_read2_b32 v[72:73], v11 offset0:69 offset1:77
	ds_read2_b32 v[74:75], v11 offset0:134 offset1:142
	ds_read2_b32 v[76:77], v11 offset0:199 offset1:207
	v_or_b32_e32 v0, s0, v18
	v_lshlrev_b32_e32 v0, 9, v0
	s_waitcnt lgkmcnt(6)
	v_cvt_pk_bf16_f32 v60, v64, v14
	s_waitcnt lgkmcnt(4)
	v_cvt_pk_bf16_f32 v61, v66, v68
	s_waitcnt lgkmcnt(2)
	v_cvt_pk_bf16_f32 v62, v70, v72
	s_waitcnt lgkmcnt(0)
	v_cvt_pk_bf16_f32 v63, v74, v76
	v_lshl_add_u64 v[80:81], v[78:79], 0, v[0:1]
	global_store_dwordx4 v[80:81], v[60:63], off sc1
	v_or_b32_e32 v0, s0, v20
	v_lshlrev_b32_e32 v0, 9, v0
	v_cvt_pk_bf16_f32 v60, v65, v15
	v_cvt_pk_bf16_f32 v61, v67, v69
	v_cvt_pk_bf16_f32 v62, v71, v73
	v_cvt_pk_bf16_f32 v63, v75, v77
	ds_read2_b32 v[64:65], v19 offset0:81 offset1:89
	ds_read2_b32 v[66:67], v19 offset0:16 offset1:24
	ds_read2_b32 v[68:69], v19 offset0:146 offset1:154
	ds_read2_b32 v[70:71], v19 offset0:211 offset1:219
	ds_read2_b32 v[72:73], v11 offset0:20 offset1:28
	ds_read2_b32 v[74:75], v11 offset0:85 offset1:93
	ds_read2_b32 v[76:77], v11 offset0:150 offset1:158
	ds_read2_b32 v[80:81], v11 offset0:215 offset1:223
	v_lshl_add_u64 v[14:15], v[78:79], 0, v[0:1]
	v_or_b32_e32 v0, s0, v21
	v_lshlrev_b32_e32 v0, 9, v0
	global_store_dwordx4 v[14:15], v[60:63], off sc1
	v_lshl_add_u64 v[14:15], v[78:79], 0, v[0:1]
	v_or_b32_e32 v0, s0, v22
	s_waitcnt lgkmcnt(6)
	v_cvt_pk_bf16_f32 v60, v66, v64
	s_waitcnt lgkmcnt(4)
	v_cvt_pk_bf16_f32 v61, v68, v70
	s_waitcnt lgkmcnt(2)
	v_cvt_pk_bf16_f32 v62, v72, v74
	s_waitcnt lgkmcnt(0)
	v_cvt_pk_bf16_f32 v63, v76, v80
	global_store_dwordx4 v[14:15], v[60:63], off sc1
	v_lshlrev_b32_e32 v0, 9, v0
	v_lshl_add_u64 v[14:15], v[78:79], 0, v[0:1]
	v_cvt_pk_bf16_f32 v60, v67, v65
	v_cvt_pk_bf16_f32 v61, v69, v71
	v_cvt_pk_bf16_f32 v62, v73, v75
	v_cvt_pk_bf16_f32 v63, v77, v81
	ds_read2_b32 v[64:65], v19 offset0:32 offset1:40
	ds_read2_b32 v[66:67], v19 offset0:97 offset1:105
	ds_read2_b32 v[68:69], v19 offset0:162 offset1:170
	ds_read2_b32 v[70:71], v19 offset0:227 offset1:235
	ds_read2_b32 v[72:73], v11 offset0:36 offset1:44
	ds_read2_b32 v[74:75], v11 offset0:101 offset1:109
	ds_read2_b32 v[76:77], v11 offset0:166 offset1:174
	ds_read2_b32 v[80:81], v11 offset0:231 offset1:239
	v_or_b32_e32 v0, s0, v23
	v_lshlrev_b32_e32 v0, 9, v0
	global_store_dwordx4 v[14:15], v[60:63], off sc1
	v_lshl_add_u64 v[14:15], v[78:79], 0, v[0:1]
	v_or_b32_e32 v0, s0, v24
	s_waitcnt lgkmcnt(6)
	v_cvt_pk_bf16_f32 v60, v64, v66
	s_waitcnt lgkmcnt(4)
	v_cvt_pk_bf16_f32 v61, v68, v70
	s_waitcnt lgkmcnt(2)
	v_cvt_pk_bf16_f32 v62, v72, v74
	s_waitcnt lgkmcnt(0)
	v_cvt_pk_bf16_f32 v63, v76, v80
	global_store_dwordx4 v[14:15], v[60:63], off sc1
	v_lshlrev_b32_e32 v0, 9, v0
	v_lshl_add_u64 v[14:15], v[78:79], 0, v[0:1]
	v_cvt_pk_bf16_f32 v60, v65, v67
	v_cvt_pk_bf16_f32 v61, v69, v71
	v_cvt_pk_bf16_f32 v62, v73, v75
	v_cvt_pk_bf16_f32 v63, v77, v81
	ds_read2_b32 v[64:65], v19 offset0:48 offset1:56
	ds_read2_b32 v[66:67], v19 offset0:113 offset1:121
	ds_read2_b32 v[68:69], v19 offset0:178 offset1:186
	ds_read2_b32 v[70:71], v19 offset0:243 offset1:251
	ds_read2_b32 v[72:73], v11 offset0:52 offset1:60
	ds_read2_b32 v[74:75], v11 offset0:117 offset1:125
	ds_read2_b32 v[76:77], v11 offset0:182 offset1:190
	ds_read2_b32 v[80:81], v11 offset0:247 offset1:255
	v_or_b32_e32 v0, s0, v25
	v_lshlrev_b32_e32 v0, 9, v0
	global_store_dwordx4 v[14:15], v[60:63], off sc1
	v_lshl_add_u64 v[14:15], v[78:79], 0, v[0:1]
	v_or_b32_e32 v0, s0, v26
	s_waitcnt lgkmcnt(6)
	v_cvt_pk_bf16_f32 v60, v64, v66
	s_waitcnt lgkmcnt(4)
	v_cvt_pk_bf16_f32 v61, v68, v70
	s_waitcnt lgkmcnt(2)
	v_cvt_pk_bf16_f32 v62, v72, v74
	s_waitcnt lgkmcnt(0)
	v_cvt_pk_bf16_f32 v63, v76, v80
	v_lshlrev_b32_e32 v0, 9, v0
	global_store_dwordx4 v[14:15], v[60:63], off sc1
	v_lshl_add_u64 v[14:15], v[78:79], 0, v[0:1]
	s_mov_b64 s[4:5], 0
	v_cvt_pk_bf16_f32 v60, v65, v67
	v_cvt_pk_bf16_f32 v61, v69, v71
	v_cvt_pk_bf16_f32 v62, v73, v75
	v_cvt_pk_bf16_f32 v63, v77, v81
	global_store_dwordx4 v[14:15], v[60:63], off sc1
	s_waitcnt lgkmcnt(0)
.LBB0_35:
	s_andn2_b64 vcc, exec, s[4:5]
	s_cbranch_vccnz .LBB0_37
	s_add_i32 s0, s12, 0x400
	s_and_b32 s1, s18, 0x1ffc0
	s_and_b32 s0, s0, 0x7c0
	v_or_b32_e32 v0, s1, v16
	s_lshl_b32 s6, s0, 2
	v_lshl_add_u64 v[14:15], v[2:3], 0, s[6:7]
	v_lshlrev_b32_e32 v0, 13, v0
	v_lshl_add_u64 v[14:15], v[14:15], 0, v[0:1]
	v_add_co_u32_e32 v60, vcc, 0x4000, v14
	v_add_u32_e32 v0, 0x3cf0, v17
	s_nop 0
	v_addc_co_u32_e32 v61, vcc, 0, v15, vcc
	v_add_co_u32_e32 v62, vcc, 0x8000, v14
	v_add_u32_e32 v11, 0x400, v19
	s_nop 0
	v_addc_co_u32_e32 v63, vcc, 0, v15, vcc
	v_add_co_u32_e32 v64, vcc, 0xc000, v14
	s_lshl_b32 s6, s1, 1
	s_nop 0
	v_addc_co_u32_e32 v65, vcc, 0, v15, vcc
	v_add_co_u32_e32 v68, vcc, 0x10000, v14
	global_load_dwordx2 v[66:67], v[14:15], off nt
	s_nop 0
	global_load_dwordx2 v[60:61], v[60:61], off nt
	s_nop 0
	global_load_dwordx2 v[62:63], v[62:63], off nt
	s_nop 0
	global_load_dwordx2 v[64:65], v[64:65], off nt
	v_addc_co_u32_e32 v69, vcc, 0, v15, vcc
	v_add_co_u32_e32 v70, vcc, 0x14000, v14
	s_nop 1
	v_addc_co_u32_e32 v71, vcc, 0, v15, vcc
	v_add_co_u32_e32 v72, vcc, 0x18000, v14
	s_nop 1
	v_addc_co_u32_e32 v73, vcc, 0, v15, vcc
	v_add_co_u32_e32 v74, vcc, 0x1c000, v14
	s_nop 1
	v_addc_co_u32_e32 v75, vcc, 0, v15, vcc
	v_add_co_u32_e32 v76, vcc, 0x20000, v14
	global_load_dwordx2 v[68:69], v[68:69], off nt
	s_nop 0
	global_load_dwordx2 v[70:71], v[70:71], off nt
	s_nop 0
	global_load_dwordx2 v[72:73], v[72:73], off nt
	s_nop 0
	global_load_dwordx2 v[74:75], v[74:75], off nt
	v_addc_co_u32_e32 v77, vcc, 0, v15, vcc
	v_add_co_u32_e32 v78, vcc, 0x24000, v14
	s_nop 1
	v_addc_co_u32_e32 v79, vcc, 0, v15, vcc
	v_add_co_u32_e32 v80, vcc, 0x28000, v14
	s_nop 1
	v_addc_co_u32_e32 v81, vcc, 0, v15, vcc
	v_add_co_u32_e32 v82, vcc, 0x2c000, v14
	s_nop 1
	v_addc_co_u32_e32 v83, vcc, 0, v15, vcc
	v_add_co_u32_e32 v84, vcc, 0x30000, v14
	global_load_dwordx2 v[76:77], v[76:77], off nt
	s_nop 0
	global_load_dwordx2 v[78:79], v[78:79], off nt
	s_nop 0
	global_load_dwordx2 v[80:81], v[80:81], off nt
	s_nop 0
	global_load_dwordx2 v[82:83], v[82:83], off nt
	v_addc_co_u32_e32 v85, vcc, 0, v15, vcc
	v_add_co_u32_e32 v86, vcc, 0x34000, v14
	s_nop 1
	v_addc_co_u32_e32 v87, vcc, 0, v15, vcc
	v_add_co_u32_e32 v88, vcc, 0x38000, v14
	s_nop 1
	v_addc_co_u32_e32 v89, vcc, 0, v15, vcc
	v_add_co_u32_e32 v90, vcc, 0x3c000, v14
	s_nop 1
	v_addc_co_u32_e32 v91, vcc, 0, v15, vcc
	v_add_co_u32_e32 v92, vcc, 0x40000, v14
	global_load_dwordx2 v[84:85], v[84:85], off nt
	s_nop 0
	global_load_dwordx2 v[86:87], v[86:87], off nt
	s_nop 0
	global_load_dwordx2 v[88:89], v[88:89], off nt
	s_nop 0
	global_load_dwordx2 v[90:91], v[90:91], off nt
	v_addc_co_u32_e32 v93, vcc, 0, v15, vcc
	v_add_co_u32_e32 v94, vcc, 0x44000, v14
	s_nop 1
	v_addc_co_u32_e32 v95, vcc, 0, v15, vcc
	v_add_co_u32_e32 v96, vcc, 0x48000, v14
	s_nop 1
	v_addc_co_u32_e32 v97, vcc, 0, v15, vcc
	v_add_co_u32_e32 v98, vcc, 0x4c000, v14
	s_nop 1
	v_addc_co_u32_e32 v99, vcc, 0, v15, vcc
	v_add_co_u32_e32 v100, vcc, 0x50000, v14
	global_load_dwordx2 v[92:93], v[92:93], off nt
	s_nop 0
	global_load_dwordx2 v[94:95], v[94:95], off nt
	s_nop 0
	global_load_dwordx2 v[96:97], v[96:97], off nt
	s_nop 0
	global_load_dwordx2 v[98:99], v[98:99], off nt
	v_addc_co_u32_e32 v101, vcc, 0, v15, vcc
	v_add_co_u32_e32 v102, vcc, 0x54000, v14
	s_nop 1
	v_addc_co_u32_e32 v103, vcc, 0, v15, vcc
	v_add_co_u32_e32 v104, vcc, 0x58000, v14
	s_nop 1
	v_addc_co_u32_e32 v105, vcc, 0, v15, vcc
	v_add_co_u32_e32 v106, vcc, 0x5c000, v14
	s_nop 1
	v_addc_co_u32_e32 v107, vcc, 0, v15, vcc
	v_add_co_u32_e32 v108, vcc, 0x60000, v14
	global_load_dwordx2 v[100:101], v[100:101], off nt
	s_nop 0
	global_load_dwordx2 v[102:103], v[102:103], off nt
	s_nop 0
	global_load_dwordx2 v[104:105], v[104:105], off nt
	s_nop 0
	global_load_dwordx2 v[106:107], v[106:107], off nt
	v_addc_co_u32_e32 v109, vcc, 0, v15, vcc
	v_add_co_u32_e32 v110, vcc, 0x64000, v14
	s_nop 1
	v_addc_co_u32_e32 v111, vcc, 0, v15, vcc
	v_add_co_u32_e32 v112, vcc, 0x68000, v14
	s_nop 1
	v_addc_co_u32_e32 v113, vcc, 0, v15, vcc
	v_add_co_u32_e32 v114, vcc, 0x6c000, v14
	s_nop 1
	v_addc_co_u32_e32 v115, vcc, 0, v15, vcc
	v_add_co_u32_e32 v116, vcc, 0x70000, v14
	global_load_dwordx2 v[108:109], v[108:109], off nt
	s_nop 0
	global_load_dwordx2 v[110:111], v[110:111], off nt
	s_nop 0
	global_load_dwordx2 v[112:113], v[112:113], off nt
	s_nop 0
	global_load_dwordx2 v[114:115], v[114:115], off nt
	v_addc_co_u32_e32 v117, vcc, 0, v15, vcc
	v_add_co_u32_e32 v118, vcc, 0x74000, v14
	s_nop 1
	v_addc_co_u32_e32 v119, vcc, 0, v15, vcc
	v_add_co_u32_e32 v120, vcc, 0x78000, v14
	s_nop 1
	v_addc_co_u32_e32 v121, vcc, 0, v15, vcc
	v_add_co_u32_e32 v14, vcc, 0x7c000, v14
	global_load_dwordx2 v[116:117], v[116:117], off nt
	s_nop 0
	global_load_dwordx2 v[118:119], v[118:119], off nt
	s_nop 0
	global_load_dwordx2 v[120:121], v[120:121], off nt
	v_addc_co_u32_e32 v15, vcc, 0, v15, vcc
	global_load_dwordx2 v[14:15], v[14:15], off nt
	s_waitcnt vmcnt(31)
	ds_write2_b32 v17, v66, v67 offset1:1
	s_waitcnt vmcnt(30)
	ds_write2_b32 v17, v60, v61 offset0:130 offset1:131
	s_waitcnt vmcnt(29)
	ds_write2_b32 v30, v62, v63 offset1:1
	s_waitcnt vmcnt(28)
	ds_write2_b32 v31, v64, v65 offset1:1
	s_waitcnt vmcnt(27)
	ds_write2_b32 v32, v68, v69 offset1:1
	s_waitcnt vmcnt(26)
	ds_write2_b32 v33, v70, v71 offset1:1
	s_waitcnt vmcnt(25)
	ds_write2_b32 v34, v72, v73 offset1:1
	s_waitcnt vmcnt(24)
	ds_write2_b32 v35, v74, v75 offset1:1
	s_waitcnt vmcnt(23)
	ds_write2_b32 v36, v76, v77 offset1:1
	s_waitcnt vmcnt(22)
	ds_write2_b32 v37, v78, v79 offset1:1
	s_waitcnt vmcnt(21)
	ds_write2_b32 v38, v80, v81 offset1:1
	s_waitcnt vmcnt(20)
	ds_write2_b32 v39, v82, v83 offset1:1
	s_waitcnt vmcnt(19)
	ds_write2_b32 v40, v84, v85 offset1:1
	s_waitcnt vmcnt(18)
	ds_write2_b32 v41, v86, v87 offset1:1
	s_waitcnt vmcnt(17)
	ds_write2_b32 v42, v88, v89 offset1:1
	s_waitcnt vmcnt(16)
	ds_write2_b32 v43, v90, v91 offset1:1
	s_waitcnt vmcnt(15)
	ds_write2_b32 v44, v92, v93 offset1:1
	s_waitcnt vmcnt(14)
	ds_write2_b32 v45, v94, v95 offset1:1
	s_waitcnt vmcnt(13)
	ds_write2_b32 v46, v96, v97 offset1:1
	s_waitcnt vmcnt(12)
	ds_write2_b32 v47, v98, v99 offset1:1
	s_waitcnt vmcnt(11)
	ds_write2_b32 v48, v100, v101 offset1:1
	s_waitcnt vmcnt(10)
	ds_write2_b32 v49, v102, v103 offset1:1
	s_waitcnt vmcnt(9)
	ds_write2_b32 v50, v104, v105 offset1:1
	s_waitcnt vmcnt(8)
	ds_write2_b32 v51, v106, v107 offset1:1
	s_waitcnt vmcnt(7)
	ds_write2_b32 v52, v108, v109 offset1:1
	s_waitcnt vmcnt(6)
	ds_write2_b32 v53, v110, v111 offset1:1
	s_waitcnt vmcnt(5)
	ds_write2_b32 v54, v112, v113 offset1:1
	s_waitcnt vmcnt(4)
	ds_write2_b32 v55, v114, v115 offset1:1
	s_waitcnt vmcnt(3)
	ds_write2_b32 v56, v116, v117 offset1:1
	s_waitcnt vmcnt(2)
	ds_write2_b32 v57, v118, v119 offset1:1
	s_waitcnt vmcnt(1)
	ds_write2_b32 v0, v120, v121 offset1:1
	v_add_u32_e32 v0, 0x3ef8, v17
	v_lshl_add_u64 v[78:79], v[6:7], 0, s[6:7]
	s_waitcnt vmcnt(0)
	ds_write2_b32 v0, v14, v15 offset1:1
	s_waitcnt lgkmcnt(0)
	ds_read2_b32 v[14:15], v19 offset0:65 offset1:73
	ds_read2_b32 v[64:65], v19 offset1:8
	ds_read2_b32 v[66:67], v19 offset0:130 offset1:138
	ds_read2_b32 v[68:69], v19 offset0:195 offset1:203
	ds_read2_b32 v[70:71], v11 offset0:4 offset1:12
	ds_read2_b32 v[72:73], v11 offset0:69 offset1:77
	ds_read2_b32 v[74:75], v11 offset0:134 offset1:142
	ds_read2_b32 v[76:77], v11 offset0:199 offset1:207
	v_or_b32_e32 v0, s0, v18
	v_lshlrev_b32_e32 v0, 12, v0
	s_waitcnt lgkmcnt(6)
	v_cvt_pk_bf16_f32 v60, v64, v14
	s_waitcnt lgkmcnt(4)
	v_cvt_pk_bf16_f32 v61, v66, v68
	s_waitcnt lgkmcnt(2)
	v_cvt_pk_bf16_f32 v62, v70, v72
	s_waitcnt lgkmcnt(0)
	v_cvt_pk_bf16_f32 v63, v74, v76
	v_lshl_add_u64 v[80:81], v[78:79], 0, v[0:1]
	global_store_dwordx4 v[80:81], v[60:63], off sc1
	v_or_b32_e32 v0, s0, v20
	v_lshlrev_b32_e32 v0, 12, v0
	v_cvt_pk_bf16_f32 v60, v65, v15
	v_cvt_pk_bf16_f32 v61, v67, v69
	v_cvt_pk_bf16_f32 v62, v71, v73
	v_cvt_pk_bf16_f32 v63, v75, v77
	ds_read2_b32 v[64:65], v19 offset0:81 offset1:89
	ds_read2_b32 v[66:67], v19 offset0:16 offset1:24
	ds_read2_b32 v[68:69], v19 offset0:146 offset1:154
	ds_read2_b32 v[70:71], v19 offset0:211 offset1:219
	ds_read2_b32 v[72:73], v11 offset0:20 offset1:28
	ds_read2_b32 v[74:75], v11 offset0:85 offset1:93
	ds_read2_b32 v[76:77], v11 offset0:150 offset1:158
	ds_read2_b32 v[80:81], v11 offset0:215 offset1:223
	v_lshl_add_u64 v[14:15], v[78:79], 0, v[0:1]
	v_or_b32_e32 v0, s0, v21
	v_lshlrev_b32_e32 v0, 12, v0
	global_store_dwordx4 v[14:15], v[60:63], off sc1
	v_lshl_add_u64 v[14:15], v[78:79], 0, v[0:1]
	v_or_b32_e32 v0, s0, v22
	s_waitcnt lgkmcnt(6)
	v_cvt_pk_bf16_f32 v60, v66, v64
	s_waitcnt lgkmcnt(4)
	v_cvt_pk_bf16_f32 v61, v68, v70
	s_waitcnt lgkmcnt(2)
	v_cvt_pk_bf16_f32 v62, v72, v74
	s_waitcnt lgkmcnt(0)
	v_cvt_pk_bf16_f32 v63, v76, v80
	global_store_dwordx4 v[14:15], v[60:63], off sc1
	v_lshlrev_b32_e32 v0, 12, v0
	v_lshl_add_u64 v[14:15], v[78:79], 0, v[0:1]
	v_cvt_pk_bf16_f32 v60, v67, v65
	v_cvt_pk_bf16_f32 v61, v69, v71
	v_cvt_pk_bf16_f32 v62, v73, v75
	v_cvt_pk_bf16_f32 v63, v77, v81
	ds_read2_b32 v[64:65], v19 offset0:32 offset1:40
	ds_read2_b32 v[66:67], v19 offset0:97 offset1:105
	ds_read2_b32 v[68:69], v19 offset0:162 offset1:170
	ds_read2_b32 v[70:71], v19 offset0:227 offset1:235
	ds_read2_b32 v[72:73], v11 offset0:36 offset1:44
	ds_read2_b32 v[74:75], v11 offset0:101 offset1:109
	ds_read2_b32 v[76:77], v11 offset0:166 offset1:174
	ds_read2_b32 v[80:81], v11 offset0:231 offset1:239
	v_or_b32_e32 v0, s0, v23
	v_lshlrev_b32_e32 v0, 12, v0
	global_store_dwordx4 v[14:15], v[60:63], off sc1
	v_lshl_add_u64 v[14:15], v[78:79], 0, v[0:1]
	v_or_b32_e32 v0, s0, v24
	s_waitcnt lgkmcnt(6)
	v_cvt_pk_bf16_f32 v60, v64, v66
	s_waitcnt lgkmcnt(4)
	v_cvt_pk_bf16_f32 v61, v68, v70
	s_waitcnt lgkmcnt(2)
	v_cvt_pk_bf16_f32 v62, v72, v74
	s_waitcnt lgkmcnt(0)
	v_cvt_pk_bf16_f32 v63, v76, v80
	global_store_dwordx4 v[14:15], v[60:63], off sc1
	v_lshlrev_b32_e32 v0, 12, v0
	v_lshl_add_u64 v[14:15], v[78:79], 0, v[0:1]
	v_cvt_pk_bf16_f32 v60, v65, v67
	v_cvt_pk_bf16_f32 v61, v69, v71
	v_cvt_pk_bf16_f32 v62, v73, v75
	v_cvt_pk_bf16_f32 v63, v77, v81
	ds_read2_b32 v[64:65], v19 offset0:48 offset1:56
	ds_read2_b32 v[66:67], v19 offset0:113 offset1:121
	ds_read2_b32 v[68:69], v19 offset0:178 offset1:186
	ds_read2_b32 v[70:71], v19 offset0:243 offset1:251
	ds_read2_b32 v[72:73], v11 offset0:52 offset1:60
	ds_read2_b32 v[74:75], v11 offset0:117 offset1:125
	ds_read2_b32 v[76:77], v11 offset0:182 offset1:190
	ds_read2_b32 v[80:81], v11 offset0:247 offset1:255
	v_or_b32_e32 v0, s0, v25
	v_lshlrev_b32_e32 v0, 12, v0
	global_store_dwordx4 v[14:15], v[60:63], off sc1
	v_lshl_add_u64 v[14:15], v[78:79], 0, v[0:1]
	v_or_b32_e32 v0, s0, v26
	s_waitcnt lgkmcnt(6)
	v_cvt_pk_bf16_f32 v60, v64, v66
	s_waitcnt lgkmcnt(4)
	v_cvt_pk_bf16_f32 v61, v68, v70
	s_waitcnt lgkmcnt(2)
	v_cvt_pk_bf16_f32 v62, v72, v74
	s_waitcnt lgkmcnt(0)
	v_cvt_pk_bf16_f32 v63, v76, v80
	v_lshlrev_b32_e32 v0, 12, v0
	global_store_dwordx4 v[14:15], v[60:63], off sc1
	v_lshl_add_u64 v[14:15], v[78:79], 0, v[0:1]
	s_nop 0
	v_cvt_pk_bf16_f32 v60, v65, v67
	v_cvt_pk_bf16_f32 v61, v69, v71
	v_cvt_pk_bf16_f32 v62, v73, v75
	v_cvt_pk_bf16_f32 v63, v77, v81
	global_store_dwordx4 v[14:15], v[60:63], off sc1
	s_waitcnt lgkmcnt(0)

.LBB0_38:
	s_andn2_b64 vcc, exec, s[4:5]
	s_cbranch_vccnz .LBB0_31
	s_ashr_i32 s0, s3, 31
	s_lshr_b32 s0, s0, 26
	s_add_i32 s0, s3, s0
	s_and_b32 s4, s0, 0xffffffc0
	s_lshl_b32 s0, s0, 6
	s_and_b32 s0, s0, 0xfffff000
	s_sub_i32 s0, s12, s0
	v_or_b32_e32 v60, s4, v16
	s_add_i32 s8, s0, 0x400
	v_ashrrev_i32_e32 v61, 31, v60
	v_or_b32_e32 v64, 2, v60
	v_or_b32_e32 v66, 4, v60
	v_or_b32_e32 v68, 6, v60
	v_or_b32_e32 v70, 8, v60
	v_or_b32_e32 v72, 10, v60
	v_or_b32_e32 v74, 12, v60
	v_or_b32_e32 v76, 14, v60
	v_or_b32_e32 v78, 16, v60
	v_or_b32_e32 v80, 18, v60
	v_or_b32_e32 v82, 20, v60
	v_or_b32_e32 v84, 22, v60
	v_or_b32_e32 v86, 24, v60
	v_or_b32_e32 v88, 26, v60
	v_or_b32_e32 v90, 28, v60
	v_or_b32_e32 v92, 30, v60
	v_or_b32_e32 v94, 32, v60
	v_or_b32_e32 v96, 34, v60
	v_or_b32_e32 v98, 36, v60
	v_or_b32_e32 v100, 38, v60
	v_or_b32_e32 v102, 40, v60
	v_or_b32_e32 v104, 42, v60
	v_or_b32_e32 v106, 44, v60
	v_or_b32_e32 v108, 46, v60
	v_or_b32_e32 v110, 48, v60
	v_or_b32_e32 v112, 50, v60
	v_or_b32_e32 v114, 52, v60
	v_or_b32_e32 v116, 54, v60
	v_or_b32_e32 v118, 56, v60
	v_or_b32_e32 v120, 58, v60
	v_or_b32_e32 v122, 60, v60
	s_ashr_i32 s9, s8, 31
	v_lshlrev_b64 v[62:63], 14, v[60:61]
	v_ashrrev_i32_e32 v65, 31, v64
	v_ashrrev_i32_e32 v67, 31, v66
	v_ashrrev_i32_e32 v69, 31, v68
	v_ashrrev_i32_e32 v71, 31, v70
	v_ashrrev_i32_e32 v73, 31, v72
	v_ashrrev_i32_e32 v75, 31, v74
	v_ashrrev_i32_e32 v77, 31, v76
	v_ashrrev_i32_e32 v79, 31, v78
	v_ashrrev_i32_e32 v81, 31, v80
	v_ashrrev_i32_e32 v83, 31, v82
	v_ashrrev_i32_e32 v85, 31, v84
	v_ashrrev_i32_e32 v87, 31, v86
	v_ashrrev_i32_e32 v89, 31, v88
	v_ashrrev_i32_e32 v91, 31, v90
	v_ashrrev_i32_e32 v93, 31, v92
	v_ashrrev_i32_e32 v95, 31, v94
	v_ashrrev_i32_e32 v97, 31, v96
	v_ashrrev_i32_e32 v99, 31, v98
	v_ashrrev_i32_e32 v101, 31, v100
	v_ashrrev_i32_e32 v103, 31, v102
	v_ashrrev_i32_e32 v105, 31, v104
	v_ashrrev_i32_e32 v107, 31, v106
	v_ashrrev_i32_e32 v109, 31, v108
	v_ashrrev_i32_e32 v111, 31, v110
	v_ashrrev_i32_e32 v113, 31, v112
	v_ashrrev_i32_e32 v115, 31, v114
	v_ashrrev_i32_e32 v117, 31, v116
	v_ashrrev_i32_e32 v119, 31, v118
	v_ashrrev_i32_e32 v121, 31, v120
	v_ashrrev_i32_e32 v123, 31, v122
	v_or_b32_e32 v60, 62, v60
	v_lshl_add_u64 v[14:15], s[8:9], 2, v[4:5]
	v_lshlrev_b64 v[64:65], 14, v[64:65]
	v_lshlrev_b64 v[66:67], 14, v[66:67]
	v_lshlrev_b64 v[68:69], 14, v[68:69]
	v_lshlrev_b64 v[70:71], 14, v[70:71]
	v_lshlrev_b64 v[72:73], 14, v[72:73]
	v_lshlrev_b64 v[74:75], 14, v[74:75]
	v_lshlrev_b64 v[76:77], 14, v[76:77]
	v_lshlrev_b64 v[78:79], 14, v[78:79]
	v_lshlrev_b64 v[80:81], 14, v[80:81]
	v_lshlrev_b64 v[82:83], 14, v[82:83]
	v_lshlrev_b64 v[84:85], 14, v[84:85]
	v_lshlrev_b64 v[86:87], 14, v[86:87]
	v_lshlrev_b64 v[88:89], 14, v[88:89]
	v_lshlrev_b64 v[90:91], 14, v[90:91]
	v_lshlrev_b64 v[92:93], 14, v[92:93]
	v_lshlrev_b64 v[94:95], 14, v[94:95]
	v_lshlrev_b64 v[96:97], 14, v[96:97]
	v_lshlrev_b64 v[98:99], 14, v[98:99]
	v_lshlrev_b64 v[100:101], 14, v[100:101]
	v_lshlrev_b64 v[102:103], 14, v[102:103]
	v_lshlrev_b64 v[104:105], 14, v[104:105]
	v_lshlrev_b64 v[106:107], 14, v[106:107]
	v_lshlrev_b64 v[108:109], 14, v[108:109]
	v_lshlrev_b64 v[110:111], 14, v[110:111]
	v_lshlrev_b64 v[112:113], 14, v[112:113]
	v_lshlrev_b64 v[114:115], 14, v[114:115]
	v_lshlrev_b64 v[116:117], 14, v[116:117]
	v_lshlrev_b64 v[118:119], 14, v[118:119]
	v_lshlrev_b64 v[120:121], 14, v[120:121]
	v_lshlrev_b64 v[122:123], 14, v[122:123]
	v_ashrrev_i32_e32 v61, 31, v60
	v_lshl_add_u64 v[62:63], v[14:15], 0, v[62:63]
	v_lshl_add_u64 v[64:65], v[14:15], 0, v[64:65]
	v_lshl_add_u64 v[66:67], v[14:15], 0, v[66:67]
	v_lshl_add_u64 v[68:69], v[14:15], 0, v[68:69]
	v_lshl_add_u64 v[70:71], v[14:15], 0, v[70:71]
	v_lshl_add_u64 v[72:73], v[14:15], 0, v[72:73]
	v_lshl_add_u64 v[74:75], v[14:15], 0, v[74:75]
	v_lshl_add_u64 v[76:77], v[14:15], 0, v[76:77]
	v_lshl_add_u64 v[78:79], v[14:15], 0, v[78:79]
	v_lshl_add_u64 v[80:81], v[14:15], 0, v[80:81]
	v_lshl_add_u64 v[82:83], v[14:15], 0, v[82:83]
	v_lshl_add_u64 v[84:85], v[14:15], 0, v[84:85]
	v_lshl_add_u64 v[86:87], v[14:15], 0, v[86:87]
	v_lshl_add_u64 v[88:89], v[14:15], 0, v[88:89]
	v_lshl_add_u64 v[90:91], v[14:15], 0, v[90:91]
	v_lshl_add_u64 v[92:93], v[14:15], 0, v[92:93]
	v_lshl_add_u64 v[94:95], v[14:15], 0, v[94:95]
	v_lshl_add_u64 v[96:97], v[14:15], 0, v[96:97]
	v_lshl_add_u64 v[98:99], v[14:15], 0, v[98:99]
	v_lshl_add_u64 v[100:101], v[14:15], 0, v[100:101]
	v_lshl_add_u64 v[102:103], v[14:15], 0, v[102:103]
	v_lshl_add_u64 v[104:105], v[14:15], 0, v[104:105]
	v_lshl_add_u64 v[106:107], v[14:15], 0, v[106:107]
	v_lshl_add_u64 v[108:109], v[14:15], 0, v[108:109]
	v_lshl_add_u64 v[110:111], v[14:15], 0, v[110:111]
	v_lshl_add_u64 v[112:113], v[14:15], 0, v[112:113]
	v_lshl_add_u64 v[114:115], v[14:15], 0, v[114:115]
	v_lshl_add_u64 v[116:117], v[14:15], 0, v[116:117]
	v_lshl_add_u64 v[118:119], v[14:15], 0, v[118:119]
	v_lshl_add_u64 v[120:121], v[14:15], 0, v[120:121]
	v_lshl_add_u64 v[122:123], v[14:15], 0, v[122:123]
	v_lshlrev_b64 v[60:61], 14, v[60:61]
	global_load_dwordx2 v[62:63], v[62:63], off nt
	s_nop 0
	global_load_dwordx2 v[64:65], v[64:65], off nt
	s_nop 0
	global_load_dwordx2 v[66:67], v[66:67], off nt
	s_nop 0
	global_load_dwordx2 v[68:69], v[68:69], off nt
	s_nop 0
	global_load_dwordx2 v[70:71], v[70:71], off nt
	s_nop 0
	global_load_dwordx2 v[72:73], v[72:73], off nt
	s_nop 0
	global_load_dwordx2 v[74:75], v[74:75], off nt
	s_nop 0
	global_load_dwordx2 v[76:77], v[76:77], off nt
	s_nop 0
	global_load_dwordx2 v[78:79], v[78:79], off nt
	s_nop 0
	global_load_dwordx2 v[80:81], v[80:81], off nt
	s_nop 0
	global_load_dwordx2 v[82:83], v[82:83], off nt
	s_nop 0
	global_load_dwordx2 v[84:85], v[84:85], off nt
	s_nop 0
	global_load_dwordx2 v[86:87], v[86:87], off nt
	s_nop 0
	global_load_dwordx2 v[88:89], v[88:89], off nt
	s_nop 0
	global_load_dwordx2 v[90:91], v[90:91], off nt
	s_nop 0
	global_load_dwordx2 v[92:93], v[92:93], off nt
	s_nop 0
	global_load_dwordx2 v[94:95], v[94:95], off nt
	s_nop 0
	global_load_dwordx2 v[96:97], v[96:97], off nt
	s_nop 0
	global_load_dwordx2 v[98:99], v[98:99], off nt
	s_nop 0
	global_load_dwordx2 v[100:101], v[100:101], off nt
	s_nop 0
	global_load_dwordx2 v[102:103], v[102:103], off nt
	s_nop 0
	global_load_dwordx2 v[104:105], v[104:105], off nt
	s_nop 0
	global_load_dwordx2 v[106:107], v[106:107], off nt
	s_nop 0
	global_load_dwordx2 v[108:109], v[108:109], off nt
	s_nop 0
	global_load_dwordx2 v[110:111], v[110:111], off nt
	s_nop 0
	global_load_dwordx2 v[112:113], v[112:113], off nt
	s_nop 0
	global_load_dwordx2 v[114:115], v[114:115], off nt
	s_nop 0
	global_load_dwordx2 v[116:117], v[116:117], off nt
	s_nop 0
	global_load_dwordx2 v[118:119], v[118:119], off nt
	s_nop 0
	global_load_dwordx2 v[120:121], v[120:121], off nt
	v_lshl_add_u64 v[14:15], v[14:15], 0, v[60:61]
	global_load_dwordx2 v[122:123], v[122:123], off nt
	v_add_u32_e32 v0, 0x3cf0, v17
	global_load_dwordx2 v[14:15], v[14:15], off nt
	s_waitcnt vmcnt(31)
	ds_write2_b32 v17, v62, v63 offset1:1
	s_waitcnt vmcnt(30)
	ds_write2_b32 v17, v64, v65 offset0:130 offset1:131
	s_waitcnt vmcnt(29)
	ds_write2_b32 v30, v66, v67 offset1:1
	s_waitcnt vmcnt(28)
	ds_write2_b32 v31, v68, v69 offset1:1
	s_waitcnt vmcnt(27)
	ds_write2_b32 v32, v70, v71 offset1:1
	s_waitcnt vmcnt(26)
	ds_write2_b32 v33, v72, v73 offset1:1
	s_waitcnt vmcnt(25)
	ds_write2_b32 v34, v74, v75 offset1:1
	s_waitcnt vmcnt(24)
	ds_write2_b32 v35, v76, v77 offset1:1
	s_waitcnt vmcnt(23)
	ds_write2_b32 v36, v78, v79 offset1:1
	s_waitcnt vmcnt(22)
	ds_write2_b32 v37, v80, v81 offset1:1
	s_waitcnt vmcnt(21)
	ds_write2_b32 v38, v82, v83 offset1:1
	s_waitcnt vmcnt(20)
	ds_write2_b32 v39, v84, v85 offset1:1
	s_waitcnt vmcnt(19)
	ds_write2_b32 v40, v86, v87 offset1:1
	s_waitcnt vmcnt(18)
	ds_write2_b32 v41, v88, v89 offset1:1
	s_waitcnt vmcnt(17)
	ds_write2_b32 v42, v90, v91 offset1:1
	s_waitcnt vmcnt(16)
	ds_write2_b32 v43, v92, v93 offset1:1
	s_waitcnt vmcnt(15)
	ds_write2_b32 v44, v94, v95 offset1:1
	s_waitcnt vmcnt(14)
	ds_write2_b32 v45, v96, v97 offset1:1
	s_waitcnt vmcnt(13)
	ds_write2_b32 v46, v98, v99 offset1:1
	s_waitcnt vmcnt(12)
	ds_write2_b32 v47, v100, v101 offset1:1
	s_waitcnt vmcnt(11)
	ds_write2_b32 v48, v102, v103 offset1:1
	s_waitcnt vmcnt(10)
	ds_write2_b32 v49, v104, v105 offset1:1
	s_waitcnt vmcnt(9)
	ds_write2_b32 v50, v106, v107 offset1:1
	s_waitcnt vmcnt(8)
	ds_write2_b32 v51, v108, v109 offset1:1
	s_waitcnt vmcnt(7)
	ds_write2_b32 v52, v110, v111 offset1:1
	s_waitcnt vmcnt(6)
	ds_write2_b32 v53, v112, v113 offset1:1
	s_waitcnt vmcnt(5)
	ds_write2_b32 v54, v114, v115 offset1:1
	s_waitcnt vmcnt(4)
	ds_write2_b32 v55, v116, v117 offset1:1
	s_waitcnt vmcnt(3)
	ds_write2_b32 v56, v118, v119 offset1:1
	s_waitcnt vmcnt(2)
	ds_write2_b32 v57, v120, v121 offset1:1
	s_and_b32 s1, s8, 0xffffff80
	s_waitcnt vmcnt(1)
	ds_write2_b32 v0, v122, v123 offset1:1
	v_add_u32_e32 v0, 0x3ef8, v17
	s_waitcnt vmcnt(0)
	ds_write2_b32 v0, v14, v15 offset1:1
	s_waitcnt lgkmcnt(0)
	s_and_b32 s6, s14, 16
	ds_read2_b32 v[14:15], v19 offset0:65 offset1:73
	ds_read2_b32 v[64:65], v19 offset1:8
	ds_read2_b32 v[66:67], v19 offset0:130 offset1:138
	ds_read2_b32 v[68:69], v19 offset0:195 offset1:203
	v_add_u32_e32 v11, s0, v18
	s_ashr_i32 s5, s4, 31
	s_or_b32 s1, s6, s1
	v_add_u32_e32 v13, 0x400, v11
	v_add_u32_e32 v0, 0x400, v19
	v_or_b32_e32 v82, s1, v18
	v_cmp_gt_i32_e32 vcc, s52, v13
	s_cmpk_lt_u32 s0, 0x800
	ds_read2_b32 v[70:71], v0 offset0:4 offset1:12
	ds_read2_b32 v[72:73], v0 offset0:69 offset1:77
	ds_read2_b32 v[74:75], v0 offset0:134 offset1:142
	ds_read2_b32 v[76:77], v0 offset0:199 offset1:207
	s_waitcnt lgkmcnt(6)
	v_cvt_pk_bf16_f32 v60, v64, v14
	v_cndmask_b32_e32 v14, v58, v59, vcc
	v_cndmask_b32_e32 v13, v13, v82, vcc
	s_cselect_b64 vcc, -1, 0
	v_cndmask_b32_e32 v14, 0, v14, vcc
	v_add_u32_e32 v78, v13, v14
	v_ashrrev_i32_e32 v79, 31, v78
	v_lshlrev_b64 v[78:79], 12, v[78:79]
	v_lshl_add_u64 v[80:81], s[4:5], 1, v[8:9]
	v_add_u32_e32 v13, 0x408, v11
	s_waitcnt lgkmcnt(4)
	v_cvt_pk_bf16_f32 v61, v66, v68
	s_waitcnt lgkmcnt(2)
	v_cvt_pk_bf16_f32 v62, v70, v72
	s_waitcnt lgkmcnt(0)
	v_cvt_pk_bf16_f32 v63, v74, v76
	v_lshl_add_u64 v[78:79], v[80:81], 0, v[78:79]
	v_cmp_gt_i32_e64 s[4:5], s52, v13
	global_store_dwordx4 v[78:79], v[60:63], off sc1
	v_or_b32_e32 v14, s1, v20
	v_cndmask_b32_e64 v13, v13, v14, s[4:5]
	v_cvt_pk_bf16_f32 v60, v65, v15
	v_cndmask_b32_e64 v15, v58, v59, s[4:5]
	v_cndmask_b32_e32 v14, 0, v15, vcc
	v_add_u32_e32 v14, v13, v14
	v_ashrrev_i32_e32 v15, 31, v14
	v_lshlrev_b64 v[14:15], 12, v[14:15]
	v_cvt_pk_bf16_f32 v61, v67, v69
	v_cvt_pk_bf16_f32 v62, v71, v73
	v_cvt_pk_bf16_f32 v63, v75, v77
	v_lshl_add_u64 v[14:15], v[80:81], 0, v[14:15]
	ds_read2_b32 v[64:65], v19 offset0:16 offset1:24
	ds_read2_b32 v[66:67], v19 offset0:81 offset1:89
	ds_read2_b32 v[68:69], v19 offset0:146 offset1:154
	ds_read2_b32 v[70:71], v19 offset0:211 offset1:219
	ds_read2_b32 v[72:73], v0 offset0:20 offset1:28
	ds_read2_b32 v[74:75], v0 offset0:85 offset1:93
	global_store_dwordx4 v[14:15], v[60:63], off sc1
	ds_read2_b32 v[14:15], v0 offset0:150 offset1:158
	ds_read2_b32 v[76:77], v0 offset0:215 offset1:223
	v_add_u32_e32 v13, 0x410, v11
	v_cmp_gt_i32_e64 s[4:5], s52, v13
	s_waitcnt lgkmcnt(6)
	v_cvt_pk_bf16_f32 v60, v64, v66
	v_or_b32_e32 v63, 32, v82
	v_cndmask_b32_e64 v64, v58, v59, s[4:5]
	v_cndmask_b32_e64 v13, v13, v63, s[4:5]
	s_waitcnt lgkmcnt(0)
	v_cvt_pk_bf16_f32 v63, v14, v76
	v_cndmask_b32_e32 v14, 0, v64, vcc
	v_add_u32_e32 v78, v13, v14
	v_ashrrev_i32_e32 v79, 31, v78
	v_lshlrev_b64 v[78:79], 12, v[78:79]
	v_add_u32_e32 v13, 0x418, v11
	v_cvt_pk_bf16_f32 v61, v68, v70
	v_cvt_pk_bf16_f32 v62, v72, v74
	v_lshl_add_u64 v[78:79], v[80:81], 0, v[78:79]
	v_cmp_gt_i32_e64 s[4:5], s52, v13
	global_store_dwordx4 v[78:79], v[60:63], off sc1
	v_or_b32_e32 v14, s1, v27
	v_cndmask_b32_e64 v13, v13, v14, s[4:5]
	v_cvt_pk_bf16_f32 v63, v15, v77
	v_cndmask_b32_e64 v15, v58, v59, s[4:5]
	v_cndmask_b32_e32 v14, 0, v15, vcc
	v_add_u32_e32 v14, v13, v14
	v_ashrrev_i32_e32 v15, 31, v14
	v_lshlrev_b64 v[14:15], 12, v[14:15]
	v_cvt_pk_bf16_f32 v60, v65, v67
	v_cvt_pk_bf16_f32 v61, v69, v71
	v_cvt_pk_bf16_f32 v62, v73, v75
	v_lshl_add_u64 v[14:15], v[80:81], 0, v[14:15]
	ds_read2_b32 v[64:65], v19 offset0:32 offset1:40
	ds_read2_b32 v[66:67], v19 offset0:97 offset1:105
	ds_read2_b32 v[68:69], v19 offset0:162 offset1:170
	ds_read2_b32 v[70:71], v19 offset0:227 offset1:235
	ds_read2_b32 v[72:73], v0 offset0:36 offset1:44
	ds_read2_b32 v[74:75], v0 offset0:101 offset1:109
	global_store_dwordx4 v[14:15], v[60:63], off sc1
	ds_read2_b32 v[14:15], v0 offset0:166 offset1:174
	ds_read2_b32 v[76:77], v0 offset0:231 offset1:239
	v_add_u32_e32 v13, 0x420, v11
	v_cmp_gt_i32_e64 s[4:5], s52, v13
	s_waitcnt lgkmcnt(6)
	v_cvt_pk_bf16_f32 v60, v64, v66
	v_or_b32_e32 v63, 64, v82
	v_cndmask_b32_e64 v64, v58, v59, s[4:5]
	v_cndmask_b32_e64 v13, v13, v63, s[4:5]
	s_waitcnt lgkmcnt(0)
	v_cvt_pk_bf16_f32 v63, v14, v76
	v_cndmask_b32_e32 v14, 0, v64, vcc
	v_add_u32_e32 v78, v13, v14
	v_ashrrev_i32_e32 v79, 31, v78
	v_lshlrev_b64 v[78:79], 12, v[78:79]
	v_add_u32_e32 v13, 0x428, v11
	v_cvt_pk_bf16_f32 v61, v68, v70
	v_cvt_pk_bf16_f32 v62, v72, v74
	v_lshl_add_u64 v[78:79], v[80:81], 0, v[78:79]
	v_cmp_gt_i32_e64 s[4:5], s52, v13
	global_store_dwordx4 v[78:79], v[60:63], off sc1
	v_or_b32_e32 v14, s1, v28
	v_cndmask_b32_e64 v13, v13, v14, s[4:5]
	v_cvt_pk_bf16_f32 v63, v15, v77
	v_cndmask_b32_e64 v15, v58, v59, s[4:5]
	v_cndmask_b32_e32 v14, 0, v15, vcc
	v_add_u32_e32 v14, v13, v14
	v_ashrrev_i32_e32 v15, 31, v14
	v_cvt_pk_bf16_f32 v60, v65, v67
	v_cvt_pk_bf16_f32 v61, v69, v71
	v_cvt_pk_bf16_f32 v62, v73, v75
	v_lshlrev_b64 v[14:15], 12, v[14:15]
	ds_read2_b32 v[64:65], v19 offset0:48 offset1:56
	ds_read2_b32 v[66:67], v19 offset0:113 offset1:121
	ds_read2_b32 v[68:69], v19 offset0:178 offset1:186
	ds_read2_b32 v[70:71], v19 offset0:243 offset1:251
	ds_read2_b32 v[72:73], v0 offset0:52 offset1:60
	ds_read2_b32 v[74:75], v0 offset0:117 offset1:125
	ds_read2_b32 v[76:77], v0 offset0:182 offset1:190
	ds_read2_b32 v[78:79], v0 offset0:247 offset1:255
	v_add_u32_e32 v0, 0x430, v11
	v_lshl_add_u64 v[14:15], v[80:81], 0, v[14:15]
	v_cmp_gt_i32_e64 s[4:5], s52, v0
	global_store_dwordx4 v[14:15], v[60:63], off sc1
	v_or_b32_e32 v13, 0x60, v82
	v_cndmask_b32_e64 v14, v58, v59, s[4:5]
	v_cndmask_b32_e64 v0, v0, v13, s[4:5]
	v_cndmask_b32_e32 v13, 0, v14, vcc
	v_add_u32_e32 v14, v0, v13
	v_add_u32_e32 v0, 0x438, v11
	v_ashrrev_i32_e32 v15, 31, v14
	v_cmp_gt_i32_e64 s[4:5], s52, v0
	v_lshlrev_b64 v[14:15], 12, v[14:15]
	v_or_b32_e32 v11, s1, v29
	v_cndmask_b32_e64 v13, v58, v59, s[4:5]
	s_waitcnt lgkmcnt(6)
	v_cvt_pk_bf16_f32 v60, v64, v66
	s_waitcnt lgkmcnt(4)
	v_cvt_pk_bf16_f32 v61, v68, v70
	s_waitcnt lgkmcnt(2)
	v_cvt_pk_bf16_f32 v62, v72, v74
	s_waitcnt lgkmcnt(0)
	v_cvt_pk_bf16_f32 v63, v76, v78
	v_lshl_add_u64 v[14:15], v[80:81], 0, v[14:15]
	v_cndmask_b32_e64 v0, v0, v11, s[4:5]
	v_cndmask_b32_e32 v11, 0, v13, vcc
	global_store_dwordx4 v[14:15], v[60:63], off sc1
	v_add_u32_e32 v14, v0, v11
	v_ashrrev_i32_e32 v15, 31, v14
	v_lshlrev_b64 v[14:15], 12, v[14:15]
	v_cvt_pk_bf16_f32 v60, v65, v67
	v_cvt_pk_bf16_f32 v61, v69, v71
	v_cvt_pk_bf16_f32 v62, v73, v75
	v_cvt_pk_bf16_f32 v63, v77, v79
	v_lshl_add_u64 v[14:15], v[80:81], 0, v[14:15]
	global_store_dwordx4 v[14:15], v[60:63], off sc1
	s_waitcnt lgkmcnt(0)
	s_branch .LBB0_31

.Lcv_gu_noload:
	s_mov_b32 s8, s22
	s_mov_b32 s9, s23
	ds_read2_b32 v[70:71], v66 offset0:0 offset1:8
	ds_read2_b32 v[72:73], v66 offset0:65 offset1:73
	ds_read2_b32 v[74:75], v66 offset0:130 offset1:138
	ds_read2_b32 v[76:77], v66 offset0:195 offset1:203
	ds_read2_b32 v[78:79], v67 offset0:0 offset1:8
	ds_read2_b32 v[80:81], v67 offset0:65 offset1:73
	ds_read2_b32 v[82:83], v67 offset0:130 offset1:138
	ds_read2_b32 v[84:85], v67 offset0:195 offset1:203
	ds_read2_b32 v[86:87], v66 offset0:16 offset1:24
	ds_read2_b32 v[88:89], v66 offset0:81 offset1:89
	ds_read2_b32 v[90:91], v66 offset0:146 offset1:154
	ds_read2_b32 v[92:93], v66 offset0:211 offset1:219
	ds_read2_b32 v[94:95], v67 offset0:16 offset1:24
	ds_read2_b32 v[96:97], v67 offset0:81 offset1:89
	ds_read2_b32 v[98:99], v67 offset0:146 offset1:154
	ds_read2_b32 v[100:101], v67 offset0:211 offset1:219
	s_waitcnt lgkmcnt(8)
	v_cvt_pk_bf16_f32 v102, v70, v72
	v_cvt_pk_bf16_f32 v103, v74, v76
	v_cvt_pk_bf16_f32 v104, v78, v80
	v_cvt_pk_bf16_f32 v105, v82, v84
	v_cvt_pk_bf16_f32 v106, v71, v73
	v_cvt_pk_bf16_f32 v107, v75, v77
	v_cvt_pk_bf16_f32 v108, v79, v81
	v_cvt_pk_bf16_f32 v109, v83, v85
	global_store_dwordx4 v68, v[102:105], s[8:9] sc1
	s_add_u32 s8, s8, 0x8000
	s_addc_u32 s9, s9, 0
	global_store_dwordx4 v68, v[106:109], s[8:9] sc1
	s_add_u32 s8, s8, 0x18000
	s_addc_u32 s9, s9, 0
	ds_read2_b32 v[70:71], v66 offset0:32 offset1:40
	ds_read2_b32 v[72:73], v66 offset0:97 offset1:105
	ds_read2_b32 v[74:75], v66 offset0:162 offset1:170
	ds_read2_b32 v[76:77], v66 offset0:227 offset1:235
	ds_read2_b32 v[78:79], v67 offset0:32 offset1:40
	ds_read2_b32 v[80:81], v67 offset0:97 offset1:105
	ds_read2_b32 v[82:83], v67 offset0:162 offset1:170
	ds_read2_b32 v[84:85], v67 offset0:227 offset1:235
	s_waitcnt lgkmcnt(8)
	v_cvt_pk_bf16_f32 v102, v86, v88
	v_cvt_pk_bf16_f32 v103, v90, v92
	v_cvt_pk_bf16_f32 v104, v94, v96
	v_cvt_pk_bf16_f32 v105, v98, v100
	v_cvt_pk_bf16_f32 v106, v87, v89
	v_cvt_pk_bf16_f32 v107, v91, v93
	v_cvt_pk_bf16_f32 v108, v95, v97
	v_cvt_pk_bf16_f32 v109, v99, v101
	global_store_dwordx4 v68, v[102:105], s[8:9] sc1
	s_add_u32 s8, s8, 0x8000
	s_addc_u32 s9, s9, 0
	global_store_dwordx4 v68, v[106:109], s[8:9] sc1
	s_add_u32 s8, s8, 0x18000
	s_addc_u32 s9, s9, 0
	ds_read2_b32 v[86:87], v66 offset0:48 offset1:56
	ds_read2_b32 v[88:89], v66 offset0:113 offset1:121
	ds_read2_b32 v[90:91], v66 offset0:178 offset1:186
	ds_read2_b32 v[92:93], v66 offset0:243 offset1:251
	ds_read2_b32 v[94:95], v67 offset0:48 offset1:56
	ds_read2_b32 v[96:97], v67 offset0:113 offset1:121
	ds_read2_b32 v[98:99], v67 offset0:178 offset1:186
	ds_read2_b32 v[100:101], v67 offset0:243 offset1:251
	s_waitcnt lgkmcnt(8)
	v_cvt_pk_bf16_f32 v102, v70, v72
	v_cvt_pk_bf16_f32 v103, v74, v76
	v_cvt_pk_bf16_f32 v104, v78, v80
	v_cvt_pk_bf16_f32 v105, v82, v84
	v_cvt_pk_bf16_f32 v106, v71, v73
	v_cvt_pk_bf16_f32 v107, v75, v77
	v_cvt_pk_bf16_f32 v108, v79, v81
	v_cvt_pk_bf16_f32 v109, v83, v85
	global_store_dwordx4 v68, v[102:105], s[8:9] sc1
	s_add_u32 s8, s8, 0x8000
	s_addc_u32 s9, s9, 0
	global_store_dwordx4 v68, v[106:109], s[8:9] sc1
	s_add_u32 s8, s8, 0x18000
	s_addc_u32 s9, s9, 0
	s_waitcnt lgkmcnt(0)
	v_cvt_pk_bf16_f32 v102, v86, v88
	v_cvt_pk_bf16_f32 v103, v90, v92
	v_cvt_pk_bf16_f32 v104, v94, v96
	v_cvt_pk_bf16_f32 v105, v98, v100
	v_cvt_pk_bf16_f32 v106, v87, v89
	v_cvt_pk_bf16_f32 v107, v91, v93
	v_cvt_pk_bf16_f32 v108, v95, v97
	v_cvt_pk_bf16_f32 v109, v99, v101
	global_store_dwordx4 v68, v[102:105], s[8:9] sc1
	s_add_u32 s8, s8, 0x8000
	s_addc_u32 s9, s9, 0
	global_store_dwordx4 v68, v[106:109], s[8:9] sc1
	s_cmp_lt_u32 s16, 0x1600
	s_cbranch_scc1 .Lcv_gu_top

.Lcv_wde_noload:
	s_mov_b32 s8, s22
	s_mov_b32 s9, s23
	ds_read2_b32 v[70:71], v66 offset0:0 offset1:8
	ds_read2_b32 v[72:73], v66 offset0:65 offset1:73
	ds_read2_b32 v[74:75], v66 offset0:130 offset1:138
	ds_read2_b32 v[76:77], v66 offset0:195 offset1:203
	ds_read2_b32 v[78:79], v67 offset0:0 offset1:8
	ds_read2_b32 v[80:81], v67 offset0:65 offset1:73
	ds_read2_b32 v[82:83], v67 offset0:130 offset1:138
	ds_read2_b32 v[84:85], v67 offset0:195 offset1:203
	ds_read2_b32 v[86:87], v66 offset0:16 offset1:24
	ds_read2_b32 v[88:89], v66 offset0:81 offset1:89
	ds_read2_b32 v[90:91], v66 offset0:146 offset1:154
	ds_read2_b32 v[92:93], v66 offset0:211 offset1:219
	ds_read2_b32 v[94:95], v67 offset0:16 offset1:24
	ds_read2_b32 v[96:97], v67 offset0:81 offset1:89
	ds_read2_b32 v[98:99], v67 offset0:146 offset1:154
	ds_read2_b32 v[100:101], v67 offset0:211 offset1:219
	s_waitcnt lgkmcnt(8)
	v_cvt_pk_bf16_f32 v102, v70, v72
	v_cvt_pk_bf16_f32 v103, v74, v76
	v_cvt_pk_bf16_f32 v104, v78, v80
	v_cvt_pk_bf16_f32 v105, v82, v84
	v_cvt_pk_bf16_f32 v106, v71, v73
	v_cvt_pk_bf16_f32 v107, v75, v77
	v_cvt_pk_bf16_f32 v108, v79, v81
	v_cvt_pk_bf16_f32 v109, v83, v85
	global_store_dwordx4 v68, v[102:105], s[8:9] sc1
	s_add_u32 s8, s8, 0x16000
	s_addc_u32 s9, s9, 0
	global_store_dwordx4 v68, v[106:109], s[8:9] sc1
	s_add_u32 s8, s8, 0x16000
	s_addc_u32 s9, s9, 0
	ds_read2_b32 v[70:71], v66 offset0:32 offset1:40
	ds_read2_b32 v[72:73], v66 offset0:97 offset1:105
	ds_read2_b32 v[74:75], v66 offset0:162 offset1:170
	ds_read2_b32 v[76:77], v66 offset0:227 offset1:235
	ds_read2_b32 v[78:79], v67 offset0:32 offset1:40
	ds_read2_b32 v[80:81], v67 offset0:97 offset1:105
	ds_read2_b32 v[82:83], v67 offset0:162 offset1:170
	ds_read2_b32 v[84:85], v67 offset0:227 offset1:235
	s_waitcnt lgkmcnt(8)
	v_cvt_pk_bf16_f32 v102, v86, v88
	v_cvt_pk_bf16_f32 v103, v90, v92
	v_cvt_pk_bf16_f32 v104, v94, v96
	v_cvt_pk_bf16_f32 v105, v98, v100
	v_cvt_pk_bf16_f32 v106, v87, v89
	v_cvt_pk_bf16_f32 v107, v91, v93
	v_cvt_pk_bf16_f32 v108, v95, v97
	v_cvt_pk_bf16_f32 v109, v99, v101
	global_store_dwordx4 v68, v[102:105], s[8:9] sc1
	s_add_u32 s8, s8, 0x16000
	s_addc_u32 s9, s9, 0
	global_store_dwordx4 v68, v[106:109], s[8:9] sc1
	s_add_u32 s8, s8, 0x16000
	s_addc_u32 s9, s9, 0
	ds_read2_b32 v[86:87], v66 offset0:48 offset1:56
	ds_read2_b32 v[88:89], v66 offset0:113 offset1:121
	ds_read2_b32 v[90:91], v66 offset0:178 offset1:186
	ds_read2_b32 v[92:93], v66 offset0:243 offset1:251
	ds_read2_b32 v[94:95], v67 offset0:48 offset1:56
	ds_read2_b32 v[96:97], v67 offset0:113 offset1:121
	ds_read2_b32 v[98:99], v67 offset0:178 offset1:186
	ds_read2_b32 v[100:101], v67 offset0:243 offset1:251
	s_waitcnt lgkmcnt(8)
	v_cvt_pk_bf16_f32 v102, v70, v72
	v_cvt_pk_bf16_f32 v103, v74, v76
	v_cvt_pk_bf16_f32 v104, v78, v80
	v_cvt_pk_bf16_f32 v105, v82, v84
	v_cvt_pk_bf16_f32 v106, v71, v73
	v_cvt_pk_bf16_f32 v107, v75, v77
	v_cvt_pk_bf16_f32 v108, v79, v81
	v_cvt_pk_bf16_f32 v109, v83, v85
	global_store_dwordx4 v68, v[102:105], s[8:9] sc1
	s_add_u32 s8, s8, 0x16000
	s_addc_u32 s9, s9, 0
	global_store_dwordx4 v68, v[106:109], s[8:9] sc1
	s_add_u32 s8, s8, 0x16000
	s_addc_u32 s9, s9, 0
	s_waitcnt lgkmcnt(0)
	v_cvt_pk_bf16_f32 v102, v86, v88
	v_cvt_pk_bf16_f32 v103, v90, v92
	v_cvt_pk_bf16_f32 v104, v94, v96
	v_cvt_pk_bf16_f32 v105, v98, v100
	v_cvt_pk_bf16_f32 v106, v87, v89
	v_cvt_pk_bf16_f32 v107, v91, v93
	v_cvt_pk_bf16_f32 v108, v95, v97
	v_cvt_pk_bf16_f32 v109, v99, v101
	global_store_dwordx4 v68, v[102:105], s[8:9] sc1
	s_add_u32 s8, s8, 0x16000
	s_addc_u32 s9, s9, 0
	global_store_dwordx4 v68, v[106:109], s[8:9] sc1
	s_cmp_lt_u32 s16, 0x300
	s_cbranch_scc1 .Lcv_wde_top

.LBB0_611:
	s_ashr_i32 s0, s6, 31
	s_lshr_b32 s0, s0, 27
	s_add_i32 s0, s6, s0
	s_ashr_i32 s1, s0, 5
	s_lshl_b32 s0, s1, 6
	s_lshl_b32 s14, s1, 11
	s_mul_i32 s15, s1, 0xff500000
	v_or_b32_e32 v40, s0, v4
	s_sub_i32 s14, s8, s14
	s_ashr_i32 s1, s0, 31
	v_add_u32_e32 v42, s15, v6
	v_or_b32_e32 v44, 2, v40
	v_or_b32_e32 v46, 4, v40
	v_or_b32_e32 v48, 6, v40
	v_or_b32_e32 v50, 8, v40
	v_or_b32_e32 v52, 10, v40
	v_or_b32_e32 v54, 12, v40
	v_or_b32_e32 v56, 14, v40
	v_or_b32_e32 v58, 16, v40
	v_or_b32_e32 v60, 18, v40
	v_or_b32_e32 v62, 20, v40
	v_or_b32_e32 v64, 22, v40
	v_or_b32_e32 v66, 24, v40
	v_or_b32_e32 v68, 26, v40
	v_or_b32_e32 v70, 28, v40
	v_or_b32_e32 v72, 30, v40
	v_or_b32_e32 v74, 32, v40
	v_or_b32_e32 v76, 34, v40
	v_or_b32_e32 v78, 36, v40
	v_or_b32_e32 v80, 38, v40
	v_or_b32_e32 v82, 40, v40
	v_or_b32_e32 v84, 42, v40
	v_or_b32_e32 v86, 44, v40
	v_or_b32_e32 v88, 46, v40
	v_or_b32_e32 v90, 48, v40
	v_or_b32_e32 v92, 50, v40
	v_or_b32_e32 v94, 52, v40
	v_or_b32_e32 v96, 54, v40
	s_ashr_i32 s15, s14, 31
	v_ashrrev_i32_e32 v41, 31, v40
	v_or_b32_e32 v98, 56, v40
	v_or_b32_e32 v100, 58, v40
	v_or_b32_e32 v102, 60, v40
	v_or_b32_e32 v104, 62, v40
	v_lshl_add_u64 v[106:107], s[0:1], 1, v[2:3]
	v_ashrrev_i32_e32 v43, 31, v42
	v_ashrrev_i32_e32 v45, 31, v44
	v_ashrrev_i32_e32 v47, 31, v46
	v_ashrrev_i32_e32 v49, 31, v48
	v_ashrrev_i32_e32 v51, 31, v50
	v_ashrrev_i32_e32 v53, 31, v52
	v_ashrrev_i32_e32 v55, 31, v54
	v_ashrrev_i32_e32 v57, 31, v56
	v_ashrrev_i32_e32 v59, 31, v58
	v_ashrrev_i32_e32 v61, 31, v60
	v_ashrrev_i32_e32 v63, 31, v62
	v_ashrrev_i32_e32 v65, 31, v64
	v_ashrrev_i32_e32 v67, 31, v66
	v_ashrrev_i32_e32 v69, 31, v68
	v_ashrrev_i32_e32 v71, 31, v70
	v_ashrrev_i32_e32 v73, 31, v72
	v_ashrrev_i32_e32 v75, 31, v74
	v_ashrrev_i32_e32 v77, 31, v76
	v_ashrrev_i32_e32 v79, 31, v78
	v_ashrrev_i32_e32 v81, 31, v80
	v_ashrrev_i32_e32 v83, 31, v82
	v_ashrrev_i32_e32 v85, 31, v84
	v_ashrrev_i32_e32 v87, 31, v86
	v_ashrrev_i32_e32 v89, 31, v88
	v_ashrrev_i32_e32 v91, 31, v90
	v_ashrrev_i32_e32 v93, 31, v92
	v_ashrrev_i32_e32 v95, 31, v94
	v_ashrrev_i32_e32 v97, 31, v96
	v_add_u32_e32 v108, 0xb000, v42
	v_add_u32_e32 v110, 0x16000, v42
	v_add_u32_e32 v112, 0x21000, v42
	v_add_u32_e32 v114, 0x2c000, v42
	v_add_u32_e32 v116, 0x37000, v42
	v_add_u32_e32 v118, 0x42000, v42
	v_add_u32_e32 v120, 0x4d000, v42
	v_lshl_add_u64 v[122:123], s[14:15], 2, v[0:1]
	v_lshlrev_b64 v[40:41], 13, v[40:41]
	v_ashrrev_i32_e32 v99, 31, v98
	v_ashrrev_i32_e32 v101, 31, v100
	v_ashrrev_i32_e32 v103, 31, v102
	v_ashrrev_i32_e32 v105, 31, v104
	v_lshl_add_u64 v[124:125], v[42:43], 1, v[106:107]
	v_lshlrev_b64 v[42:43], 13, v[44:45]
	v_lshlrev_b64 v[44:45], 13, v[46:47]
	v_lshlrev_b64 v[46:47], 13, v[48:49]
	v_lshlrev_b64 v[48:49], 13, v[50:51]
	v_lshlrev_b64 v[50:51], 13, v[52:53]
	v_lshlrev_b64 v[52:53], 13, v[54:55]
	v_lshlrev_b64 v[54:55], 13, v[56:57]
	v_lshlrev_b64 v[56:57], 13, v[58:59]
	v_lshlrev_b64 v[58:59], 13, v[60:61]
	v_lshlrev_b64 v[60:61], 13, v[62:63]
	v_lshlrev_b64 v[62:63], 13, v[64:65]
	v_lshlrev_b64 v[64:65], 13, v[66:67]
	v_lshlrev_b64 v[66:67], 13, v[68:69]
	v_lshlrev_b64 v[68:69], 13, v[70:71]
	v_lshlrev_b64 v[70:71], 13, v[72:73]
	v_lshlrev_b64 v[72:73], 13, v[74:75]
	v_lshlrev_b64 v[74:75], 13, v[76:77]
	v_lshlrev_b64 v[76:77], 13, v[78:79]
	v_lshlrev_b64 v[78:79], 13, v[80:81]
	v_lshlrev_b64 v[80:81], 13, v[82:83]
	v_lshlrev_b64 v[82:83], 13, v[84:85]
	v_lshlrev_b64 v[84:85], 13, v[86:87]
	v_lshlrev_b64 v[86:87], 13, v[88:89]
	v_lshlrev_b64 v[88:89], 13, v[90:91]
	v_lshlrev_b64 v[90:91], 13, v[92:93]
	v_lshlrev_b64 v[92:93], 13, v[94:95]
	v_lshlrev_b64 v[94:95], 13, v[96:97]
	v_ashrrev_i32_e32 v109, 31, v108
	v_ashrrev_i32_e32 v111, 31, v110
	v_ashrrev_i32_e32 v113, 31, v112
	v_ashrrev_i32_e32 v115, 31, v114
	v_ashrrev_i32_e32 v117, 31, v116
	v_ashrrev_i32_e32 v119, 31, v118
	v_ashrrev_i32_e32 v121, 31, v120
	v_lshl_add_u64 v[40:41], v[122:123], 0, v[40:41]
	v_lshlrev_b64 v[96:97], 13, v[98:99]
	v_lshlrev_b64 v[98:99], 13, v[100:101]
	v_lshlrev_b64 v[100:101], 13, v[102:103]
	v_lshlrev_b64 v[102:103], 13, v[104:105]
	v_lshl_add_u64 v[42:43], v[122:123], 0, v[42:43]
	v_lshl_add_u64 v[44:45], v[122:123], 0, v[44:45]
	v_lshl_add_u64 v[46:47], v[122:123], 0, v[46:47]
	v_lshl_add_u64 v[48:49], v[122:123], 0, v[48:49]
	v_lshl_add_u64 v[50:51], v[122:123], 0, v[50:51]
	v_lshl_add_u64 v[52:53], v[122:123], 0, v[52:53]
	v_lshl_add_u64 v[54:55], v[122:123], 0, v[54:55]
	v_lshl_add_u64 v[56:57], v[122:123], 0, v[56:57]
	v_lshl_add_u64 v[58:59], v[122:123], 0, v[58:59]
	v_lshl_add_u64 v[60:61], v[122:123], 0, v[60:61]
	v_lshl_add_u64 v[62:63], v[122:123], 0, v[62:63]
	v_lshl_add_u64 v[64:65], v[122:123], 0, v[64:65]
	v_lshl_add_u64 v[66:67], v[122:123], 0, v[66:67]
	v_lshl_add_u64 v[68:69], v[122:123], 0, v[68:69]
	v_lshl_add_u64 v[70:71], v[122:123], 0, v[70:71]
	v_lshl_add_u64 v[72:73], v[122:123], 0, v[72:73]
	v_lshl_add_u64 v[74:75], v[122:123], 0, v[74:75]
	v_lshl_add_u64 v[76:77], v[122:123], 0, v[76:77]
	v_lshl_add_u64 v[78:79], v[122:123], 0, v[78:79]
	v_lshl_add_u64 v[80:81], v[122:123], 0, v[80:81]
	v_lshl_add_u64 v[82:83], v[122:123], 0, v[82:83]
	v_lshl_add_u64 v[84:85], v[122:123], 0, v[84:85]
	v_lshl_add_u64 v[86:87], v[122:123], 0, v[86:87]
	v_lshl_add_u64 v[88:89], v[122:123], 0, v[88:89]
	v_lshl_add_u64 v[90:91], v[122:123], 0, v[90:91]
	v_lshl_add_u64 v[92:93], v[122:123], 0, v[92:93]
	v_lshl_add_u64 v[94:95], v[122:123], 0, v[94:95]
	v_lshl_add_u64 v[104:105], v[108:109], 1, v[106:107]
	v_lshl_add_u64 v[108:109], v[110:111], 1, v[106:107]
	v_lshl_add_u64 v[110:111], v[112:113], 1, v[106:107]
	v_lshl_add_u64 v[112:113], v[114:115], 1, v[106:107]
	v_lshl_add_u64 v[114:115], v[116:117], 1, v[106:107]
	v_lshl_add_u64 v[116:117], v[118:119], 1, v[106:107]
	v_lshl_add_u64 v[106:107], v[120:121], 1, v[106:107]
	v_lshl_add_u64 v[96:97], v[122:123], 0, v[96:97]
	v_lshl_add_u64 v[98:99], v[122:123], 0, v[98:99]
	v_lshl_add_u64 v[100:101], v[122:123], 0, v[100:101]
	v_lshl_add_u64 v[102:103], v[122:123], 0, v[102:103]
	flat_load_dwordx2 v[118:119], v[40:41] nt
	flat_load_dwordx2 v[120:121], v[42:43] nt
	flat_load_dwordx2 v[122:123], v[44:45] nt
	flat_load_dwordx2 v[126:127], v[46:47] nt
	s_nop 0
	flat_load_dwordx2 v[40:41], v[48:49] nt
	flat_load_dwordx2 v[42:43], v[50:51] nt
	flat_load_dwordx2 v[44:45], v[52:53] nt
	flat_load_dwordx2 v[46:47], v[54:55] nt
	s_nop 0
	flat_load_dwordx2 v[48:49], v[56:57] nt
	flat_load_dwordx2 v[50:51], v[58:59] nt
	flat_load_dwordx2 v[52:53], v[60:61] nt
	flat_load_dwordx2 v[54:55], v[62:63] nt
	s_nop 0
	flat_load_dwordx2 v[56:57], v[64:65] nt
	flat_load_dwordx2 v[58:59], v[66:67] nt
	flat_load_dwordx2 v[60:61], v[68:69] nt
	flat_load_dwordx2 v[62:63], v[70:71] nt
	s_nop 0
	flat_load_dwordx2 v[64:65], v[72:73] nt
	flat_load_dwordx2 v[66:67], v[74:75] nt
	flat_load_dwordx2 v[68:69], v[76:77] nt
	flat_load_dwordx2 v[70:71], v[78:79] nt
	s_nop 0
	flat_load_dwordx2 v[72:73], v[80:81] nt
	flat_load_dwordx2 v[74:75], v[82:83] nt
	flat_load_dwordx2 v[76:77], v[84:85] nt
	flat_load_dwordx2 v[78:79], v[86:87] nt
	s_nop 0
	flat_load_dwordx2 v[80:81], v[88:89] nt
	flat_load_dwordx2 v[82:83], v[90:91] nt
	flat_load_dwordx2 v[84:85], v[92:93] nt
	flat_load_dwordx2 v[86:87], v[94:95] nt
	s_nop 0
	flat_load_dwordx2 v[88:89], v[96:97] nt
	flat_load_dwordx2 v[90:91], v[98:99] nt
	flat_load_dwordx2 v[92:93], v[100:101] nt
	flat_load_dwordx2 v[94:95], v[102:103] nt
	s_waitcnt vmcnt(0) lgkmcnt(0)
	ds_write2_b32 v7, v118, v119 offset1:1
	ds_write2_b32 v7, v120, v121 offset0:130 offset1:131
	ds_write2_b32 v8, v122, v123 offset1:1
	ds_write2_b32 v9, v126, v127 offset1:1
	ds_write2_b32 v10, v40, v41 offset1:1
	ds_write2_b32 v11, v42, v43 offset1:1
	ds_write2_b32 v12, v44, v45 offset1:1
	ds_write2_b32 v13, v46, v47 offset1:1
	ds_write2_b32 v14, v48, v49 offset1:1
	ds_write2_b32 v15, v50, v51 offset1:1
	ds_write2_b32 v16, v52, v53 offset1:1
	ds_write2_b32 v17, v54, v55 offset1:1
	ds_write2_b32 v18, v56, v57 offset1:1
	ds_write2_b32 v19, v58, v59 offset1:1
	ds_write2_b32 v20, v60, v61 offset1:1
	ds_write2_b32 v21, v62, v63 offset1:1
	ds_write2_b32 v22, v64, v65 offset1:1
	ds_write2_b32 v23, v66, v67 offset1:1
	ds_write2_b32 v24, v68, v69 offset1:1
	ds_write2_b32 v25, v70, v71 offset1:1
	ds_write2_b32 v26, v72, v73 offset1:1
	ds_write2_b32 v27, v74, v75 offset1:1
	ds_write2_b32 v28, v76, v77 offset1:1
	ds_write2_b32 v29, v78, v79 offset1:1
	ds_write2_b32 v30, v80, v81 offset1:1
	ds_write2_b32 v31, v82, v83 offset1:1
	ds_write2_b32 v32, v84, v85 offset1:1
	ds_write2_b32 v33, v86, v87 offset1:1
	ds_write2_b32 v34, v88, v89 offset1:1
	ds_write2_b32 v35, v90, v91 offset1:1
	ds_write2_b32 v36, v92, v93 offset1:1
	ds_write2_b32 v37, v94, v95 offset1:1
	s_waitcnt lgkmcnt(0)
	ds_read2_b32 v[44:45], v5 offset0:65 offset1:73
	ds_read2_b32 v[46:47], v5 offset1:8
	ds_read2_b32 v[48:49], v5 offset0:130 offset1:138
	ds_read2_b32 v[50:51], v5 offset0:195 offset1:203
	ds_read2_b32 v[52:53], v38 offset0:4 offset1:12
	ds_read2_b32 v[54:55], v38 offset0:69 offset1:77
	ds_read2_b32 v[56:57], v38 offset0:134 offset1:142
	ds_read2_b32 v[58:59], v38 offset0:199 offset1:207
	ds_read2_b32 v[60:61], v5 offset0:81 offset1:89
	ds_read2_b32 v[62:63], v5 offset0:16 offset1:24
	ds_read2_b32 v[64:65], v5 offset0:146 offset1:154
	ds_read2_b32 v[66:67], v5 offset0:211 offset1:219
	ds_read2_b32 v[68:69], v38 offset0:20 offset1:28
	ds_read2_b32 v[70:71], v38 offset0:85 offset1:93
	ds_read2_b32 v[72:73], v38 offset0:150 offset1:158
	ds_read2_b32 v[74:75], v38 offset0:215 offset1:223
	ds_read2_b32 v[76:77], v5 offset0:32 offset1:40
	ds_read2_b32 v[78:79], v5 offset0:97 offset1:105
	ds_read2_b32 v[80:81], v5 offset0:162 offset1:170
	ds_read2_b32 v[82:83], v5 offset0:227 offset1:235
	ds_read2_b32 v[84:85], v38 offset0:36 offset1:44
	ds_read2_b32 v[86:87], v38 offset0:101 offset1:109
	ds_read2_b32 v[88:89], v38 offset0:166 offset1:174
	ds_read2_b32 v[90:91], v38 offset0:231 offset1:239
	ds_read2_b32 v[92:93], v5 offset0:48 offset1:56
	ds_read2_b32 v[94:95], v5 offset0:113 offset1:121
	ds_read2_b32 v[96:97], v5 offset0:178 offset1:186
	ds_read2_b32 v[98:99], v5 offset0:243 offset1:251
	ds_read2_b32 v[100:101], v38 offset0:52 offset1:60
	ds_read2_b32 v[102:103], v38 offset0:117 offset1:125
	ds_read2_b32 v[118:119], v38 offset0:182 offset1:190
	ds_read2_b32 v[120:121], v38 offset0:247 offset1:255
	s_waitcnt lgkmcnt(14)
	v_cvt_pk_bf16_f32 v40, v46, v44
	v_cvt_pk_bf16_f32 v41, v48, v50
	v_cvt_pk_bf16_f32 v42, v52, v54
	v_cvt_pk_bf16_f32 v43, v56, v58
	v_cvt_pk_bf16_f32 v44, v47, v45
	v_cvt_pk_bf16_f32 v45, v49, v51
	v_cvt_pk_bf16_f32 v46, v53, v55
	v_cvt_pk_bf16_f32 v47, v57, v59
	v_cvt_pk_bf16_f32 v48, v62, v60
	v_cvt_pk_bf16_f32 v49, v64, v66
	v_cvt_pk_bf16_f32 v50, v68, v70
	v_cvt_pk_bf16_f32 v51, v72, v74
	v_cvt_pk_bf16_f32 v52, v63, v61
	v_cvt_pk_bf16_f32 v53, v65, v67
	v_cvt_pk_bf16_f32 v54, v69, v71
	v_cvt_pk_bf16_f32 v55, v73, v75
	v_cvt_pk_bf16_f32 v56, v76, v78
	s_waitcnt lgkmcnt(12)
	v_cvt_pk_bf16_f32 v57, v80, v82
	s_waitcnt lgkmcnt(10)
	v_cvt_pk_bf16_f32 v58, v84, v86
	s_waitcnt lgkmcnt(8)
	v_cvt_pk_bf16_f32 v59, v88, v90
	v_cvt_pk_bf16_f32 v60, v77, v79
	v_cvt_pk_bf16_f32 v61, v81, v83
	v_cvt_pk_bf16_f32 v62, v85, v87
	v_cvt_pk_bf16_f32 v63, v89, v91
	s_waitcnt lgkmcnt(6)
	v_cvt_pk_bf16_f32 v64, v92, v94
	s_waitcnt lgkmcnt(4)
	v_cvt_pk_bf16_f32 v65, v96, v98
	s_waitcnt lgkmcnt(2)
	v_cvt_pk_bf16_f32 v66, v100, v102
	s_waitcnt lgkmcnt(0)
	v_cvt_pk_bf16_f32 v67, v118, v120
	v_cvt_pk_bf16_f32 v68, v93, v95
	v_cvt_pk_bf16_f32 v69, v97, v99
	v_cvt_pk_bf16_f32 v70, v101, v103
	v_cvt_pk_bf16_f32 v71, v119, v121
	global_store_dwordx4 v[124:125], v[40:43], off sc1
	global_store_dwordx4 v[104:105], v[44:47], off sc1
	global_store_dwordx4 v[108:109], v[48:51], off sc1
	global_store_dwordx4 v[110:111], v[52:55], off sc1
	global_store_dwordx4 v[112:113], v[56:59], off sc1
	global_store_dwordx4 v[114:115], v[60:63], off sc1
	global_store_dwordx4 v[116:117], v[64:67], off sc1
	global_store_dwordx4 v[106:107], v[68:71], off sc1
	s_waitcnt lgkmcnt(0)
	s_add_i32 s6, s6, s76
	s_add_i32 s8, s8, s9
	s_cmpk_lt_i32 s6, 0xb00
	v_add_u32_e32 v6, s7, v6
	s_cbranch_scc1 .LBB0_611

.Lcv_wdl_noload:
	s_mov_b32 s8, s22
	s_mov_b32 s9, s23
	ds_read2_b32 v[70:71], v66 offset0:0 offset1:8
	ds_read2_b32 v[72:73], v66 offset0:65 offset1:73
	ds_read2_b32 v[74:75], v66 offset0:130 offset1:138
	ds_read2_b32 v[76:77], v66 offset0:195 offset1:203
	ds_read2_b32 v[78:79], v67 offset0:0 offset1:8
	ds_read2_b32 v[80:81], v67 offset0:65 offset1:73
	ds_read2_b32 v[82:83], v67 offset0:130 offset1:138
	ds_read2_b32 v[84:85], v67 offset0:195 offset1:203
	ds_read2_b32 v[86:87], v66 offset0:16 offset1:24
	ds_read2_b32 v[88:89], v66 offset0:81 offset1:89
	ds_read2_b32 v[90:91], v66 offset0:146 offset1:154
	ds_read2_b32 v[92:93], v66 offset0:211 offset1:219
	ds_read2_b32 v[94:95], v67 offset0:16 offset1:24
	ds_read2_b32 v[96:97], v67 offset0:81 offset1:89
	ds_read2_b32 v[98:99], v67 offset0:146 offset1:154
	ds_read2_b32 v[100:101], v67 offset0:211 offset1:219
	s_waitcnt lgkmcnt(8)
	v_cvt_pk_bf16_f32 v102, v70, v72
	v_cvt_pk_bf16_f32 v103, v74, v76
	v_cvt_pk_bf16_f32 v104, v78, v80
	v_cvt_pk_bf16_f32 v105, v82, v84
	v_cvt_pk_bf16_f32 v106, v71, v73
	v_cvt_pk_bf16_f32 v107, v75, v77
	v_cvt_pk_bf16_f32 v108, v79, v81
	v_cvt_pk_bf16_f32 v109, v83, v85
	global_store_dwordx4 v68, v[102:105], s[8:9] sc1
	s_add_u32 s8, s8, 0x16000
	s_addc_u32 s9, s9, 0
	global_store_dwordx4 v68, v[106:109], s[8:9] sc1
	s_add_u32 s8, s8, 0x16000
	s_addc_u32 s9, s9, 0
	ds_read2_b32 v[70:71], v66 offset0:32 offset1:40
	ds_read2_b32 v[72:73], v66 offset0:97 offset1:105
	ds_read2_b32 v[74:75], v66 offset0:162 offset1:170
	ds_read2_b32 v[76:77], v66 offset0:227 offset1:235
	ds_read2_b32 v[78:79], v67 offset0:32 offset1:40
	ds_read2_b32 v[80:81], v67 offset0:97 offset1:105
	ds_read2_b32 v[82:83], v67 offset0:162 offset1:170
	ds_read2_b32 v[84:85], v67 offset0:227 offset1:235
	s_waitcnt lgkmcnt(8)
	v_cvt_pk_bf16_f32 v102, v86, v88
	v_cvt_pk_bf16_f32 v103, v90, v92
	v_cvt_pk_bf16_f32 v104, v94, v96
	v_cvt_pk_bf16_f32 v105, v98, v100
	v_cvt_pk_bf16_f32 v106, v87, v89
	v_cvt_pk_bf16_f32 v107, v91, v93
	v_cvt_pk_bf16_f32 v108, v95, v97
	v_cvt_pk_bf16_f32 v109, v99, v101
	global_store_dwordx4 v68, v[102:105], s[8:9] sc1
	s_add_u32 s8, s8, 0x16000
	s_addc_u32 s9, s9, 0
	global_store_dwordx4 v68, v[106:109], s[8:9] sc1
	s_add_u32 s8, s8, 0x16000
	s_addc_u32 s9, s9, 0
	ds_read2_b32 v[86:87], v66 offset0:48 offset1:56
	ds_read2_b32 v[88:89], v66 offset0:113 offset1:121
	ds_read2_b32 v[90:91], v66 offset0:178 offset1:186
	ds_read2_b32 v[92:93], v66 offset0:243 offset1:251
	ds_read2_b32 v[94:95], v67 offset0:48 offset1:56
	ds_read2_b32 v[96:97], v67 offset0:113 offset1:121
	ds_read2_b32 v[98:99], v67 offset0:178 offset1:186
	ds_read2_b32 v[100:101], v67 offset0:243 offset1:251
	s_waitcnt lgkmcnt(8)
	v_cvt_pk_bf16_f32 v102, v70, v72
	v_cvt_pk_bf16_f32 v103, v74, v76
	v_cvt_pk_bf16_f32 v104, v78, v80
	v_cvt_pk_bf16_f32 v105, v82, v84
	v_cvt_pk_bf16_f32 v106, v71, v73
	v_cvt_pk_bf16_f32 v107, v75, v77
	v_cvt_pk_bf16_f32 v108, v79, v81
	v_cvt_pk_bf16_f32 v109, v83, v85
	global_store_dwordx4 v68, v[102:105], s[8:9] sc1
	s_add_u32 s8, s8, 0x16000
	s_addc_u32 s9, s9, 0
	global_store_dwordx4 v68, v[106:109], s[8:9] sc1
	s_add_u32 s8, s8, 0x16000
	s_addc_u32 s9, s9, 0
	s_waitcnt lgkmcnt(0)
	v_cvt_pk_bf16_f32 v102, v86, v88
	v_cvt_pk_bf16_f32 v103, v90, v92
	v_cvt_pk_bf16_f32 v104, v94, v96
	v_cvt_pk_bf16_f32 v105, v98, v100
	v_cvt_pk_bf16_f32 v106, v87, v89
	v_cvt_pk_bf16_f32 v107, v91, v93
	v_cvt_pk_bf16_f32 v108, v95, v97
	v_cvt_pk_bf16_f32 v109, v99, v101
	global_store_dwordx4 v68, v[102:105], s[8:9] sc1
	s_add_u32 s8, s8, 0x16000
	s_addc_u32 s9, s9, 0
	global_store_dwordx4 v68, v[106:109], s[8:9] sc1
	s_cmp_lt_u32 s16, 0xb00
	s_cbranch_scc1 .Lcv_wdl_top
